# P3 scan: first two S^T fragment reads of every step issued right after the publishing barrier (second into v[250:253], v252 parked)
# baseline (speedup 1.0000x reference)
; DEV void gdn_scan_item(const Params& p, int item, unsigned char* lds) {
;     int tid = threadIdx.x & 255; asm volatile("" : "+v"(tid)); const int lane = tid & 63, w = tid >> 6, fr = lane & 15, fq = lane >> 4;
;     const int s = item & 7, bh = item >> 3;
;     const int b = bh >> 3, h = bh & 7;
;     bf16_t* ST = (bf16_t*)lds;
;     bf16_t* VT = ST + 16 * QS;
;     const char* bW = (const char*)((const bf16_t*)(p.ws + WS_GW) + (size_t)bh * 32 * 8192);
;     const char* bQ = (const char*)((const bf16_t*)(p.ws + WS_GQ) + (size_t)bh * 32 * 8192);
;     const char* bK = (const char*)((const bf16_t*)(p.ws + WS_GKT) + (size_t)bh * 32 * 8192);
;     const char* bA = (const char*)((const bf16_t*)(p.ws + WS_GA) + (size_t)bh * 32 * 4096);
;     const char* bU = (const char*)((const float*)(p.ws + WS_GU) + (size_t)bh * 32 * 8192);
;     const float* gE = (const float*)(p.ws + WS_GE) + bh * 32;
;     float* obuf = (float*)(p.ws + WS_O);
;     f32x4 S0 = {0.f, 0.f, 0.f, 0.f}, S1 = {0.f, 0.f, 0.f, 0.f};
;     for (int i = tid; i < 16 * QS / 2; i += 256) ((unsigned*)ST)[i] = 0u;
.LBB0_883:
	s_andn2_b64 vcc, exec, s[4:5]
	s_cbranch_vccnz .LBB0_890
	v_mov_b32_e32 v254, v252
	v_and_b32_e32 v90, 0xff, v0
	s_load_dwordx2 s[8:9], s[0:1], 0xc8
	s_movk_i32 s4, 0x440
	v_cmp_gt_i32_e32 vcc, s4, v90
	s_and_saveexec_b64 s[4:5], vcc
	s_cbranch_execz .LBB0_887
	v_lshl_add_u32 v1, v90, 2, s70
	v_add_u32_e32 v2, 0xffffff00, v90
	s_mov_b64 s[6:7], 0
	v_mov_b32_e32 v3, 0
	s_movk_i32 s10, 0x33f

.LBB0_888:
	ds_read_b128 v[246:249], v237
	ds_read_b128 v[250:253], v237 offset:64
	v_lshl_add_u64 v[214:215], s[8:9], 0, v[196:197]
	v_add_co_u32_e32 v98, vcc, s25, v214
	v_lshl_add_u64 v[216:217], s[8:9], 0, v[198:199]
	s_nop 0
	v_addc_co_u32_e32 v99, vcc, 0, v215, vcc
	v_add_co_u32_e32 v102, vcc, s26, v214
	v_lshl_add_u64 v[218:219], s[8:9], 0, v[200:201]
	s_nop 0
	v_addc_co_u32_e32 v103, vcc, 0, v215, vcc
	v_add_co_u32_e32 v106, vcc, s25, v216
	v_lshl_add_u64 v[220:221], s[8:9], 0, v[202:203]
	s_nop 0
	v_addc_co_u32_e32 v107, vcc, 0, v217, vcc
	v_add_co_u32_e32 v110, vcc, s26, v216
	v_lshl_add_u64 v[222:223], s[8:9], 0, v[194:195]
	s_nop 0
	v_addc_co_u32_e32 v111, vcc, 0, v217, vcc
	v_add_co_u32_e32 v114, vcc, s25, v218
	v_lshl_add_u64 v[224:225], s[8:9], 0, v[204:205]
	s_nop 0
	v_addc_co_u32_e32 v115, vcc, 0, v219, vcc
	v_add_co_u32_e32 v118, vcc, s26, v218
	global_load_dwordx4 v[98:101], v[98:99], off
	s_nop 0
	v_addc_co_u32_e32 v119, vcc, 0, v219, vcc
	v_add_co_u32_e32 v122, vcc, s25, v220
	global_load_dwordx4 v[102:105], v[102:103], off
	s_nop 0
	v_addc_co_u32_e32 v123, vcc, 0, v221, vcc
	v_add_co_u32_e32 v126, vcc, s26, v220
	global_load_dwordx4 v[106:109], v[106:107], off
	s_nop 0
	v_addc_co_u32_e32 v127, vcc, 0, v221, vcc
	v_add_co_u32_e32 v130, vcc, s27, v222
	global_load_dwordx4 v[110:113], v[110:111], off
	s_nop 0
	v_addc_co_u32_e32 v131, vcc, 0, v223, vcc
	global_load_dwordx4 v[114:117], v[114:115], off
	v_lshl_add_u64 v[226:227], s[8:9], 0, v[206:207]
	global_load_dwordx4 v[118:121], v[118:119], off
	v_lshl_add_u64 v[228:229], s[8:9], 0, v[208:209]
	global_load_dwordx4 v[122:125], v[122:123], off
	v_lshl_add_u64 v[230:231], s[8:9], 0, v[210:211]
	global_load_dwordx4 v[126:129], v[126:127], off
	s_nop 0
	global_load_dword v241, v[130:131], off
	global_load_dword v242, v[130:131], off offset:256
	global_load_dword v243, v[130:131], off offset:512
	global_load_dword v244, v[130:131], off offset:768
	v_add_co_u32_e32 v130, vcc, s34, v224
	v_lshl_add_u64 v[232:233], s[8:9], 0, v[212:213]
	s_nop 0
	v_addc_co_u32_e32 v131, vcc, 0, v225, vcc
	v_add_co_u32_e32 v134, vcc, s34, v226
	global_load_dwordx4 v[130:133], v[130:131], off
	s_nop 0
	v_addc_co_u32_e32 v135, vcc, 0, v227, vcc
	v_add_co_u32_e32 v146, vcc, s35, v228
	global_load_dwordx4 v[134:137], v[134:135], off
	s_nop 0
	v_addc_co_u32_e32 v147, vcc, 0, v229, vcc
	v_add_co_u32_e32 v142, vcc, s35, v230
	global_load_dwordx4 v[138:141], v[146:147], off
	s_nop 0
	v_addc_co_u32_e32 v143, vcc, 0, v231, vcc
	global_load_dwordx4 v[142:145], v[142:143], off
	s_nop 0
	global_load_dwordx4 v[146:149], v[146:147], off offset:1024

	s_waitcnt vmcnt(37) lgkmcnt(0)
	v_mfma_f32_16x16x32_bf16 v[18:21], v[18:21], v[246:249], 0
	v_add_co_u32_e32 v150, vcc, s35, v232
	s_add_i32 s61, s62, 6
	s_waitcnt vmcnt(31)
	v_mfma_f32_16x16x32_bf16 v[38:41], v[38:41], v[246:249], 0

	v_addc_co_u32_e32 v151, vcc, 0, v233, vcc
	s_waitcnt lgkmcnt(0)
	v_mfma_f32_16x16x32_bf16 v[6:9], v[6:9], v[250:253], v[18:21]
	global_load_dwordx4 v[150:153], v[150:151], off
	s_nop 1
	ds_read_b128 v[18:21], v237 offset:128
	s_add_i32 s65, s62, 7
	v_mfma_f32_16x16x32_bf16 v[2:5], v[2:5], v[250:253], v[38:41]
	v_readlane_b32 s64, v177, s61
	v_readlane_b32 s66, v177, s65
	s_add_i32 s63, s62, 8
	s_waitcnt vmcnt(27) lgkmcnt(0)
	v_mfma_f32_16x16x32_bf16 v[2:5], v[14:17], v[18:21], v[2:5]
	ds_read_b128 v[14:17], v237 offset:192
	v_lshl_add_u64 v[194:195], v[194:195], 0, s[16:17]
	v_lshl_add_u64 v[196:197], v[196:197], 0, s[18:19]
	s_waitcnt vmcnt(21)
	v_mfma_f32_16x16x32_bf16 v[6:9], v[26:29], v[18:21], v[6:9]
	v_mul_f32_e64 v20, v92, s64
	v_mul_f32_e64 v21, v93, s64
	v_pk_mul_f32 v[18:19], v[90:91], s[64:65] op_sel_hi:[1,0]
	v_lshl_add_u64 v[198:199], v[198:199], 0, s[18:19]
	s_waitcnt vmcnt(19) lgkmcnt(0)
	v_mfma_f32_16x16x32_bf16 v[6:9], v[22:25], v[14:17], v[6:9]
	v_lshl_add_u64 v[200:201], v[200:201], 0, s[18:19]
	v_lshl_add_u64 v[202:203], v[202:203], 0, s[18:19]
	v_lshl_add_u64 v[204:205], v[204:205], 0, s[20:21]
	v_mfma_f32_16x16x32_bf16 v[2:5], v[10:13], v[14:17], v[2:5]
	v_mul_f32_e64 v16, v96, s64
	v_mul_f32_e64 v17, v97, s64
	s_nop 1
	v_sub_f32_e32 v9, v240, v9
	v_sub_f32_e32 v8, v239, v8
	v_sub_f32_e32 v7, v238, v7
	v_sub_f32_e32 v6, v193, v6
	v_cvt_pk_bf16_f32 v6, v6, v7
	v_cvt_pk_bf16_f32 v7, v8, v9
	ds_write_b64 v236, v[6:7] offset:4352
	s_waitcnt lgkmcnt(0)
	s_barrier
	ds_read_b128 v[6:9], v235 offset:4352
	ds_read_b128 v[10:13], v235 offset:4416
	v_pk_mul_f32 v[14:15], v[94:95], s[64:65] op_sel_hi:[1,0]
	s_waitcnt lgkmcnt(1)
	v_mfma_f32_16x16x32_bf16 v[2:5], v[86:89], v[6:9], v[2:5]
	v_ashrrev_i32_e32 v193, 31, v192
	s_add_i32 s64, s62, 9
	s_add_i32 s65, s62, 10
	v_mfma_f32_16x16x32_bf16 v[14:17], v[70:73], v[6:9], v[14:17]
	v_readlane_b32 s64, v177, s64
	s_add_i32 s62, s62, 11
	v_readlane_b32 s62, v177, s62
	v_mfma_f32_16x16x32_bf16 v[6:9], v[66:69], v[6:9], v[18:21]
	v_lshl_add_u64 v[206:207], v[206:207], 0, s[20:21]
	v_lshl_add_u64 v[208:209], v[208:209], 0, s[18:19]
	v_lshl_add_u64 v[210:211], v[210:211], 0, s[18:19]
	s_waitcnt lgkmcnt(0)
	v_mfma_f32_16x16x32_bf16 v[90:93], v[82:85], v[10:13], v[14:17]
	v_lshl_add_u64 v[212:213], v[212:213], 0, s[18:19]
	s_cmp_lt_u32 s61, 24
	v_mfma_f32_16x16x32_bf16 v[94:97], v[78:81], v[10:13], v[6:9]
	v_mfma_f32_16x16x32_bf16 v[2:5], v[74:77], v[10:13], v[2:5]
	s_nop 3
	v_cvt_pk_bf16_f32 v6, v90, v91
	v_cvt_pk_bf16_f32 v7, v92, v93
	s_nop 0
	v_cvt_pk_bf16_f32 v8, v94, v95
	v_cvt_pk_bf16_f32 v9, v96, v97
	ds_write2_b64 v234, v[6:7], v[8:9] offset1:4
	v_lshlrev_b64 v[6:7], 12, v[192:193]
	v_lshl_add_u64 v[6:7], v[190:191], 0, v[6:7]
	v_add_co_u32_e32 v8, vcc, s30, v6
	global_store_dword v[6:7], v2, off
	s_nop 0
	v_addc_co_u32_e32 v9, vcc, 0, v7, vcc
	v_add_co_u32_e32 v2, vcc, s31, v6
	global_store_dword v[8:9], v3, off offset:-4096
	global_store_dword v[8:9], v4, off
	v_addc_co_u32_e32 v3, vcc, 0, v7, vcc
	global_store_dword v[2:3], v5, off
	v_add_co_u32_e32 v2, vcc, s36, v214
	s_waitcnt lgkmcnt(0)
	s_barrier
	ds_read_b128 v[246:249], v237
	ds_read_b128 v[250:253], v237 offset:64
	s_nop 0
	v_addc_co_u32_e32 v3, vcc, 0, v215, vcc
	v_add_co_u32_e32 v6, vcc, s37, v214
	global_load_dwordx4 v[2:5], v[2:3], off
	s_nop 0
	v_addc_co_u32_e32 v7, vcc, 0, v215, vcc
	v_add_co_u32_e32 v10, vcc, s36, v216
	global_load_dwordx4 v[6:9], v[6:7], off
	s_nop 0
	v_addc_co_u32_e32 v11, vcc, 0, v217, vcc
	v_add_co_u32_e32 v14, vcc, s37, v216
	global_load_dwordx4 v[10:13], v[10:11], off
	s_nop 0
	v_addc_co_u32_e32 v15, vcc, 0, v217, vcc
	v_add_co_u32_e32 v18, vcc, s36, v218
	global_load_dwordx4 v[14:17], v[14:15], off
	s_nop 0
	v_addc_co_u32_e32 v19, vcc, 0, v219, vcc
	v_add_co_u32_e32 v22, vcc, s37, v218
	global_load_dwordx4 v[18:21], v[18:19], off
	s_nop 0
	v_addc_co_u32_e32 v23, vcc, 0, v219, vcc
	v_add_co_u32_e32 v26, vcc, s36, v220
	global_load_dwordx4 v[22:25], v[22:23], off
	s_nop 0
	v_addc_co_u32_e32 v27, vcc, 0, v221, vcc
	v_add_co_u32_e32 v38, vcc, s37, v220
	global_load_dwordx4 v[26:29], v[26:27], off
	s_nop 0
	v_addc_co_u32_e32 v39, vcc, 0, v221, vcc
	v_add_co_u32_e32 v66, vcc, s38, v222
	global_load_dwordx4 v[38:41], v[38:39], off
	s_nop 0
	v_addc_co_u32_e32 v67, vcc, 0, v223, vcc
	global_load_dword v193, v[66:67], off
	global_load_dword v238, v[66:67], off offset:256
	global_load_dword v239, v[66:67], off offset:512
	global_load_dword v240, v[66:67], off offset:768
	v_add_co_u32_e32 v66, vcc, s39, v224
	s_nop 1
	v_addc_co_u32_e32 v67, vcc, 0, v225, vcc
	v_add_co_u32_e32 v70, vcc, s39, v226
	global_load_dwordx4 v[66:69], v[66:67], off
	s_nop 0
	v_addc_co_u32_e32 v71, vcc, 0, v227, vcc
	v_add_co_u32_e32 v82, vcc, s40, v228
	global_load_dwordx4 v[74:77], v[70:71], off
	s_nop 0
	v_addc_co_u32_e32 v83, vcc, 0, v229, vcc
	v_add_co_u32_e32 v78, vcc, s40, v230
	global_load_dwordx4 v[70:73], v[82:83], off
	s_nop 0
	v_addc_co_u32_e32 v79, vcc, 0, v231, vcc
	global_load_dwordx4 v[78:81], v[78:79], off
	s_nop 0
	global_load_dwordx4 v[82:85], v[82:83], off offset:1024

	s_waitcnt lgkmcnt(0)
	v_mfma_f32_16x16x32_bf16 v[30:33], v[30:33], v[246:249], 0
	v_add_co_u32_e32 v86, vcc, s40, v232
	v_mfma_f32_16x16x32_bf16 v[34:37], v[34:37], v[246:249], 0

	s_nop 0
	v_addc_co_u32_e32 v87, vcc, 0, v233, vcc
	s_waitcnt lgkmcnt(0)
	v_mfma_f32_16x16x32_bf16 v[30:33], v[46:49], v[250:253], v[30:33]
	ds_read_b128 v[46:49], v237 offset:128
	global_load_dwordx4 v[86:89], v[86:87], off
	s_waitcnt lgkmcnt(0)
	v_mfma_f32_16x16x32_bf16 v[30:33], v[42:45], v[46:49], v[30:33]
	ds_read_b128 v[42:45], v237 offset:192
	v_mfma_f32_16x16x32_bf16 v[34:37], v[50:53], v[250:253], v[34:37]
	v_mul_f32_e64 v52, v96, s66
	v_mul_f32_e64 v53, v97, s66
	v_pk_mul_f32 v[50:51], v[94:95], s[66:67] op_sel_hi:[1,0]
	s_waitcnt lgkmcnt(0)
	v_mfma_f32_16x16x32_bf16 v[30:33], v[58:61], v[42:45], v[30:33]
	v_mfma_f32_16x16x32_bf16 v[34:37], v[54:57], v[46:49], v[34:37]
	v_mul_f32_e64 v48, v92, s66
	v_mul_f32_e64 v49, v93, s66
	s_nop 4
	v_sub_f32_e32 v33, v156, v33
	v_sub_f32_e32 v32, v155, v32
	v_sub_f32_e32 v31, v154, v31
	s_waitcnt vmcnt(40)
	v_sub_f32_e32 v30, v157, v30
	v_cvt_pk_bf16_f32 v30, v30, v31
	v_cvt_pk_bf16_f32 v31, v32, v33
	ds_write_b64 v236, v[30:31] offset:4352
	s_waitcnt lgkmcnt(0)
	s_barrier
	v_mfma_f32_16x16x32_bf16 v[34:37], v[62:65], v[42:45], v[34:37]
	ds_read_b128 v[30:33], v235 offset:4352
	ds_read_b128 v[42:45], v235 offset:4416
	v_pk_mul_f32 v[46:47], v[90:91], s[66:67] op_sel_hi:[1,0]
	v_readlane_b32 s66, v177, s63
	s_waitcnt vmcnt(27) lgkmcnt(1)
	v_mfma_f32_16x16x32_bf16 v[34:37], v[130:133], v[30:33], v[34:37]
	s_waitcnt vmcnt(25)
	v_mfma_f32_16x16x32_bf16 v[46:49], v[138:141], v[30:33], v[46:49]
	s_waitcnt vmcnt(23)
	v_mfma_f32_16x16x32_bf16 v[30:33], v[146:149], v[30:33], v[50:53]
	s_waitcnt lgkmcnt(0)
	v_mfma_f32_16x16x32_bf16 v[90:93], v[142:145], v[42:45], v[46:49]
	s_waitcnt vmcnt(22)
	v_mfma_f32_16x16x32_bf16 v[94:97], v[150:153], v[42:45], v[30:33]
	v_mfma_f32_16x16x32_bf16 v[34:37], v[134:137], v[42:45], v[34:37]
	s_nop 4
	v_cvt_pk_bf16_f32 v30, v90, v91
	v_cvt_pk_bf16_f32 v31, v92, v93
	v_cvt_pk_bf16_f32 v32, v94, v95
	v_cvt_pk_bf16_f32 v33, v96, v97
	ds_write2_b64 v234, v[30:31], v[32:33] offset1:4
	v_add_u32_e32 v30, 64, v192
	v_ashrrev_i32_e32 v31, 31, v30
	v_lshlrev_b64 v[30:31], 12, v[30:31]
	v_lshl_add_u64 v[30:31], v[190:191], 0, v[30:31]
	v_add_co_u32_e32 v32, vcc, s30, v30
	global_store_dword v[30:31], v34, off
	s_nop 0
	v_addc_co_u32_e32 v33, vcc, 0, v31, vcc
	v_add_co_u32_e32 v30, vcc, s31, v30
	global_store_dword v[32:33], v35, off offset:-4096
	global_store_dword v[32:33], v36, off
	v_addc_co_u32_e32 v31, vcc, 0, v31, vcc
	global_store_dword v[30:31], v37, off
	v_add_co_u32_e32 v30, vcc, s41, v214
	s_waitcnt lgkmcnt(0)
	s_barrier
	ds_read_b128 v[154:157], v237
	ds_read_b128 v[250:253], v237 offset:64
	s_nop 0
	v_addc_co_u32_e32 v31, vcc, 0, v215, vcc
	v_add_co_u32_e32 v34, vcc, s42, v214
	global_load_dwordx4 v[30:33], v[30:31], off
	s_nop 0
	v_addc_co_u32_e32 v35, vcc, 0, v215, vcc
	v_add_co_u32_e32 v42, vcc, s41, v216
	global_load_dwordx4 v[34:37], v[34:35], off
	s_nop 0
	v_addc_co_u32_e32 v43, vcc, 0, v217, vcc
	v_add_co_u32_e32 v46, vcc, s42, v216
	global_load_dwordx4 v[42:45], v[42:43], off
	s_nop 0
	v_addc_co_u32_e32 v47, vcc, 0, v217, vcc
	v_add_co_u32_e32 v50, vcc, s41, v218
	global_load_dwordx4 v[46:49], v[46:47], off
	s_nop 0
	v_addc_co_u32_e32 v51, vcc, 0, v219, vcc
	v_add_co_u32_e32 v54, vcc, s42, v218
	global_load_dwordx4 v[50:53], v[50:51], off
	s_nop 0
	v_addc_co_u32_e32 v55, vcc, 0, v219, vcc
	v_add_co_u32_e32 v58, vcc, s41, v220
	global_load_dwordx4 v[54:57], v[54:55], off
	s_nop 0
	v_addc_co_u32_e32 v59, vcc, 0, v221, vcc
	v_add_co_u32_e32 v62, vcc, s42, v220
	global_load_dwordx4 v[58:61], v[58:59], off
	s_nop 0
	v_addc_co_u32_e32 v63, vcc, 0, v221, vcc
	v_add_co_u32_e32 v130, vcc, s43, v222
	global_load_dwordx4 v[62:65], v[62:63], off
	s_nop 0
	v_addc_co_u32_e32 v131, vcc, 0, v223, vcc
	global_load_dword v245, v[130:131], off
	global_load_dword v246, v[130:131], off offset:256
	global_load_dword v247, v[130:131], off offset:512
	global_load_dword v248, v[130:131], off offset:768
	v_add_co_u32_e32 v130, vcc, s44, v224
	s_nop 1
	v_addc_co_u32_e32 v131, vcc, 0, v225, vcc
	v_add_co_u32_e32 v134, vcc, s44, v226
	global_load_dwordx4 v[130:133], v[130:131], off
	s_nop 0
	v_addc_co_u32_e32 v135, vcc, 0, v227, vcc
	v_add_co_u32_e32 v146, vcc, s45, v228
	global_load_dwordx4 v[138:141], v[134:135], off
	s_nop 0
	v_addc_co_u32_e32 v147, vcc, 0, v229, vcc
	v_add_co_u32_e32 v142, vcc, s45, v230
	global_load_dwordx4 v[134:137], v[146:147], off
	s_nop 0
	v_addc_co_u32_e32 v143, vcc, 0, v231, vcc
	global_load_dwordx4 v[142:145], v[142:143], off
	s_nop 0
	global_load_dwordx4 v[146:149], v[146:147], off offset:1024

	s_waitcnt lgkmcnt(0)
	v_mfma_f32_16x16x32_bf16 v[98:101], v[98:101], v[154:157], 0
	v_add_co_u32_e32 v150, vcc, s45, v232
	v_mfma_f32_16x16x32_bf16 v[102:105], v[102:105], v[154:157], 0

	s_nop 0
	v_addc_co_u32_e32 v151, vcc, 0, v233, vcc
	s_waitcnt lgkmcnt(0)
	v_mfma_f32_16x16x32_bf16 v[98:101], v[106:109], v[250:253], v[98:101]
	ds_read_b128 v[106:109], v237 offset:128
	global_load_dwordx4 v[150:153], v[150:151], off
	v_mfma_f32_16x16x32_bf16 v[102:105], v[110:113], v[250:253], v[102:105]
	s_waitcnt lgkmcnt(0)
	v_mfma_f32_16x16x32_bf16 v[98:101], v[114:117], v[106:109], v[98:101]
	v_mfma_f32_16x16x32_bf16 v[102:105], v[118:121], v[106:109], v[102:105]
	ds_read_b128 v[106:109], v237 offset:192
	s_waitcnt lgkmcnt(0)
	v_mfma_f32_16x16x32_bf16 v[98:101], v[122:125], v[106:109], v[98:101]
	v_mfma_f32_16x16x32_bf16 v[102:105], v[126:129], v[106:109], v[102:105]
	s_nop 6
	v_sub_f32_e32 v101, v244, v101
	v_sub_f32_e32 v100, v243, v100
	v_sub_f32_e32 v99, v242, v99
	v_sub_f32_e32 v98, v241, v98
	v_cvt_pk_bf16_f32 v98, v98, v99
	v_cvt_pk_bf16_f32 v99, v100, v101
	ds_write_b64 v236, v[98:99] offset:4352
	s_waitcnt lgkmcnt(0)
	s_barrier
	ds_read_b128 v[98:101], v235 offset:4352
	ds_read_b128 v[106:109], v235 offset:4416
	s_waitcnt vmcnt(27) lgkmcnt(1)
	v_mfma_f32_16x16x32_bf16 v[66:69], v[66:69], v[98:101], v[102:105]
	s_waitcnt vmcnt(26) lgkmcnt(0)
	v_mfma_f32_16x16x32_bf16 v[66:69], v[74:77], v[106:109], v[66:69]
	v_mul_f32_e64 v76, v92, s66
	v_mul_f32_e64 v77, v93, s66
	v_pk_mul_f32 v[74:75], v[90:91], s[66:67] op_sel_hi:[1,0]
	v_pk_mul_f32 v[92:93], v[96:97], s[66:67] op_sel_hi:[1,0]
	v_pk_mul_f32 v[90:91], v[94:95], s[66:67] op_sel_hi:[1,0]
	s_waitcnt vmcnt(25)
	v_mfma_f32_16x16x32_bf16 v[70:73], v[70:73], v[98:101], v[74:77]
	s_waitcnt vmcnt(24)
	v_mfma_f32_16x16x32_bf16 v[122:125], v[78:81], v[106:109], v[70:73]
	s_waitcnt vmcnt(23)
	v_mfma_f32_16x16x32_bf16 v[70:73], v[82:85], v[98:101], v[90:93]
	s_waitcnt vmcnt(22)
	v_mfma_f32_16x16x32_bf16 v[126:129], v[86:89], v[106:109], v[70:73]
	s_nop 5
	v_cvt_pk_bf16_f32 v70, v122, v123
	v_cvt_pk_bf16_f32 v71, v124, v125
	v_cvt_pk_bf16_f32 v72, v126, v127
	v_cvt_pk_bf16_f32 v73, v128, v129
	ds_write2_b64 v234, v[70:71], v[72:73] offset1:4
	v_add_u32_e32 v70, 0x80, v192
	v_ashrrev_i32_e32 v71, 31, v70
	v_lshlrev_b64 v[70:71], 12, v[70:71]
	v_lshl_add_u64 v[70:71], v[190:191], 0, v[70:71]
	v_add_co_u32_e32 v72, vcc, s30, v70
	global_store_dword v[70:71], v66, off
	s_nop 0
	v_addc_co_u32_e32 v73, vcc, 0, v71, vcc
	v_add_co_u32_e32 v66, vcc, s31, v70
	global_store_dword v[72:73], v67, off offset:-4096
	global_store_dword v[72:73], v68, off
	v_addc_co_u32_e32 v67, vcc, 0, v71, vcc
	global_store_dword v[66:67], v69, off
	v_add_co_u32_e32 v66, vcc, s46, v214
	s_waitcnt lgkmcnt(0)
	s_barrier
	ds_read_b128 v[154:157], v237
	ds_read_b128 v[250:253], v237 offset:64
	s_nop 0
	v_addc_co_u32_e32 v67, vcc, 0, v215, vcc
	global_load_dwordx4 v[90:93], v[66:67], off
	v_add_co_u32_e32 v66, vcc, s47, v214
	s_nop 1
	v_addc_co_u32_e32 v67, vcc, 0, v215, vcc
	global_load_dwordx4 v[94:97], v[66:67], off
	v_add_co_u32_e32 v66, vcc, s46, v216
	s_nop 1
	v_addc_co_u32_e32 v67, vcc, 0, v217, vcc
	global_load_dwordx4 v[98:101], v[66:67], off
	v_add_co_u32_e32 v66, vcc, s47, v216
	s_nop 1
	v_addc_co_u32_e32 v67, vcc, 0, v217, vcc
	global_load_dwordx4 v[102:105], v[66:67], off
	v_add_co_u32_e32 v66, vcc, s46, v218
	s_nop 1
	v_addc_co_u32_e32 v67, vcc, 0, v219, vcc
	global_load_dwordx4 v[106:109], v[66:67], off
	v_add_co_u32_e32 v66, vcc, s47, v218
	s_nop 1
	v_addc_co_u32_e32 v67, vcc, 0, v219, vcc
	global_load_dwordx4 v[110:113], v[66:67], off
	v_add_co_u32_e32 v66, vcc, s46, v220
	s_nop 1
	v_addc_co_u32_e32 v67, vcc, 0, v221, vcc
	global_load_dwordx4 v[114:117], v[66:67], off
	v_add_co_u32_e32 v66, vcc, s47, v220
	s_nop 1
	v_addc_co_u32_e32 v67, vcc, 0, v221, vcc
	global_load_dwordx4 v[118:121], v[66:67], off
	v_add_co_u32_e32 v66, vcc, s48, v222
	s_nop 1
	v_addc_co_u32_e32 v67, vcc, 0, v223, vcc
	global_load_dword v241, v[66:67], off
	global_load_dword v242, v[66:67], off offset:256
	global_load_dword v243, v[66:67], off offset:512
	global_load_dword v244, v[66:67], off offset:768
	v_add_co_u32_e32 v66, vcc, s49, v224
	s_nop 1
	v_addc_co_u32_e32 v67, vcc, 0, v225, vcc
	v_add_co_u32_e32 v70, vcc, s49, v226
	global_load_dwordx4 v[66:69], v[66:67], off
	s_nop 0
	v_addc_co_u32_e32 v71, vcc, 0, v227, vcc
	v_add_co_u32_e32 v82, vcc, s50, v228
	global_load_dwordx4 v[74:77], v[70:71], off
	s_nop 0
	v_addc_co_u32_e32 v83, vcc, 0, v229, vcc
	v_add_co_u32_e32 v78, vcc, s50, v230
	global_load_dwordx4 v[70:73], v[82:83], off
	s_nop 0
	v_addc_co_u32_e32 v79, vcc, 0, v231, vcc
	global_load_dwordx4 v[78:81], v[78:79], off
	s_nop 0
	global_load_dwordx4 v[82:85], v[82:83], off offset:1024

	s_waitcnt lgkmcnt(0)
	v_mfma_f32_16x16x32_bf16 v[2:5], v[2:5], v[154:157], 0
	v_add_co_u32_e32 v86, vcc, s50, v232
	v_mfma_f32_16x16x32_bf16 v[6:9], v[6:9], v[154:157], 0

	s_nop 0
	v_addc_co_u32_e32 v87, vcc, 0, v233, vcc
	s_waitcnt lgkmcnt(0)
	v_mfma_f32_16x16x32_bf16 v[2:5], v[10:13], v[250:253], v[2:5]
	ds_read_b128 v[10:13], v237 offset:128
	global_load_dwordx4 v[86:89], v[86:87], off
	v_mfma_f32_16x16x32_bf16 v[6:9], v[14:17], v[250:253], v[6:9]
	s_waitcnt lgkmcnt(0)
	v_mfma_f32_16x16x32_bf16 v[2:5], v[18:21], v[10:13], v[2:5]
	v_mul_f32_e64 v20, v128, s64
	v_mul_f32_e64 v21, v129, s64
	v_pk_mul_f32 v[18:19], v[126:127], s[64:65] op_sel_hi:[1,0]
	v_mfma_f32_16x16x32_bf16 v[6:9], v[22:25], v[10:13], v[6:9]
	ds_read_b128 v[10:13], v237 offset:192
	s_waitcnt lgkmcnt(0)
	v_mfma_f32_16x16x32_bf16 v[2:5], v[26:29], v[10:13], v[2:5]
	v_mfma_f32_16x16x32_bf16 v[6:9], v[38:41], v[10:13], v[6:9]
	s_nop 6
	v_sub_f32_e32 v5, v240, v5
	v_sub_f32_e32 v4, v239, v4
	v_sub_f32_e32 v3, v238, v3
	v_sub_f32_e32 v2, v193, v2
	v_cvt_pk_bf16_f32 v2, v2, v3
	v_cvt_pk_bf16_f32 v3, v4, v5
	ds_write_b64 v236, v[2:3] offset:4352
	s_waitcnt lgkmcnt(0)
	s_barrier
	ds_read_b128 v[10:13], v235 offset:4352
	ds_read_b128 v[14:17], v235 offset:4416
	s_waitcnt vmcnt(27) lgkmcnt(1)
	v_mfma_f32_16x16x32_bf16 v[2:5], v[130:133], v[10:13], v[6:9]
	s_nop 2
	v_mul_f32_e64 v8, v124, s64
	v_mul_f32_e64 v9, v125, s64
	v_pk_mul_f32 v[6:7], v[122:123], s[64:65] op_sel_hi:[1,0]
	v_readlane_b32 s64, v177, s65
	s_waitcnt vmcnt(26) lgkmcnt(0)
	v_mfma_f32_16x16x32_bf16 v[2:5], v[138:141], v[14:17], v[2:5]
	s_waitcnt vmcnt(25)
	v_mfma_f32_16x16x32_bf16 v[6:9], v[134:137], v[10:13], v[6:9]
	s_waitcnt vmcnt(24)
	v_mfma_f32_16x16x32_bf16 v[154:157], v[142:145], v[14:17], v[6:9]
	s_waitcnt vmcnt(23)
	v_mfma_f32_16x16x32_bf16 v[6:9], v[146:149], v[10:13], v[18:21]
	s_waitcnt vmcnt(22)
	v_mfma_f32_16x16x32_bf16 v[146:149], v[150:153], v[14:17], v[6:9]
	s_nop 5
	v_cvt_pk_bf16_f32 v6, v154, v155
	v_cvt_pk_bf16_f32 v7, v156, v157
	v_cvt_pk_bf16_f32 v8, v146, v147
	v_cvt_pk_bf16_f32 v9, v148, v149
	ds_write2_b64 v234, v[6:7], v[8:9] offset1:4
	v_add_u32_e32 v6, 0xc0, v192
	v_ashrrev_i32_e32 v7, 31, v6
	v_lshlrev_b64 v[6:7], 12, v[6:7]
	v_lshl_add_u64 v[6:7], v[190:191], 0, v[6:7]
	v_add_co_u32_e32 v8, vcc, s30, v6
	global_store_dword v[6:7], v2, off
	s_nop 0
	v_addc_co_u32_e32 v9, vcc, 0, v7, vcc
	v_add_co_u32_e32 v2, vcc, s31, v6
	global_store_dword v[8:9], v3, off offset:-4096
	global_store_dword v[8:9], v4, off
	v_addc_co_u32_e32 v3, vcc, 0, v7, vcc
	global_store_dword v[2:3], v5, off
	v_add_co_u32_e32 v2, vcc, s51, v214
	s_waitcnt lgkmcnt(0)
	s_barrier
	ds_read_b128 v[150:153], v237
	ds_read_b128 v[250:253], v237 offset:64
	s_nop 0
	v_addc_co_u32_e32 v3, vcc, 0, v215, vcc
	global_load_dwordx4 v[18:21], v[2:3], off
	v_add_co_u32_e32 v2, vcc, s52, v214
	s_nop 1
	v_addc_co_u32_e32 v3, vcc, 0, v215, vcc
	global_load_dwordx4 v[38:41], v[2:3], off
	v_add_co_u32_e32 v2, vcc, s51, v216
	s_nop 1
	v_addc_co_u32_e32 v3, vcc, 0, v217, vcc
	global_load_dwordx4 v[6:9], v[2:3], off
	v_add_co_u32_e32 v2, vcc, s52, v216
	s_nop 1
	v_addc_co_u32_e32 v3, vcc, 0, v217, vcc
	v_add_co_u32_e32 v10, vcc, s51, v218
	global_load_dwordx4 v[2:5], v[2:3], off
	s_nop 0
	v_addc_co_u32_e32 v11, vcc, 0, v219, vcc
	global_load_dwordx4 v[26:29], v[10:11], off
	v_add_co_u32_e32 v10, vcc, s52, v218
	s_nop 1
	v_addc_co_u32_e32 v11, vcc, 0, v219, vcc
	global_load_dwordx4 v[14:17], v[10:11], off
	v_add_co_u32_e32 v10, vcc, s51, v220
	s_nop 1
	v_addc_co_u32_e32 v11, vcc, 0, v221, vcc
	global_load_dwordx4 v[22:25], v[10:11], off
	v_add_co_u32_e32 v10, vcc, s52, v220
	s_nop 1
	v_addc_co_u32_e32 v11, vcc, 0, v221, vcc
	v_add_co_u32_e32 v122, vcc, s53, v222
	global_load_dwordx4 v[10:13], v[10:11], off
	s_nop 0
	v_addc_co_u32_e32 v123, vcc, 0, v223, vcc
	global_load_dword v193, v[122:123], off
	global_load_dword v238, v[122:123], off offset:256
	global_load_dword v239, v[122:123], off offset:512
	global_load_dword v240, v[122:123], off offset:768
	v_add_co_u32_e32 v122, vcc, s54, v224
	s_nop 1
	v_addc_co_u32_e32 v123, vcc, 0, v225, vcc
	v_add_co_u32_e32 v126, vcc, s54, v226
	global_load_dwordx4 v[122:125], v[122:123], off
	s_nop 0
	v_addc_co_u32_e32 v127, vcc, 0, v227, vcc
	v_add_co_u32_e32 v138, vcc, s55, v228
	global_load_dwordx4 v[130:133], v[126:127], off
	s_nop 0
	v_addc_co_u32_e32 v139, vcc, 0, v229, vcc
	v_add_co_u32_e32 v134, vcc, s55, v230
	global_load_dwordx4 v[126:129], v[138:139], off
	s_nop 0
	v_addc_co_u32_e32 v135, vcc, 0, v231, vcc
	global_load_dwordx4 v[134:137], v[134:135], off
	s_nop 0
	global_load_dwordx4 v[138:141], v[138:139], off offset:1024

	s_waitcnt lgkmcnt(0)
	v_mfma_f32_16x16x32_bf16 v[30:33], v[30:33], v[150:153], 0
	v_add_co_u32_e32 v142, vcc, s55, v232
	v_mfma_f32_16x16x32_bf16 v[34:37], v[34:37], v[150:153], 0

	s_nop 0
	v_addc_co_u32_e32 v143, vcc, 0, v233, vcc
	s_waitcnt lgkmcnt(0)
	v_mfma_f32_16x16x32_bf16 v[30:33], v[42:45], v[250:253], v[30:33]
	ds_read_b128 v[42:45], v237 offset:128
	global_load_dwordx4 v[142:145], v[142:143], off
	v_mfma_f32_16x16x32_bf16 v[34:37], v[46:49], v[250:253], v[34:37]
	s_waitcnt lgkmcnt(0)
	v_mfma_f32_16x16x32_bf16 v[30:33], v[50:53], v[42:45], v[30:33]
	v_mul_f32_e64 v52, v148, s64
	v_mul_f32_e64 v53, v149, s64
	v_pk_mul_f32 v[50:51], v[146:147], s[64:65] op_sel_hi:[1,0]
	v_mfma_f32_16x16x32_bf16 v[34:37], v[54:57], v[42:45], v[34:37]
	ds_read_b128 v[42:45], v237 offset:192
	s_waitcnt lgkmcnt(0)
	v_mfma_f32_16x16x32_bf16 v[30:33], v[58:61], v[42:45], v[30:33]
	v_mfma_f32_16x16x32_bf16 v[34:37], v[62:65], v[42:45], v[34:37]
	s_nop 6
	v_sub_f32_e32 v33, v248, v33
	v_sub_f32_e32 v32, v247, v32
	v_sub_f32_e32 v31, v246, v31
	v_sub_f32_e32 v30, v245, v30
	v_cvt_pk_bf16_f32 v30, v30, v31
	v_cvt_pk_bf16_f32 v31, v32, v33
	ds_write_b64 v236, v[30:31] offset:4352
	s_waitcnt lgkmcnt(0)
	s_barrier
	ds_read_b128 v[42:45], v235 offset:4352
	ds_read_b128 v[46:49], v235 offset:4416
	s_waitcnt vmcnt(27) lgkmcnt(1)
	v_mfma_f32_16x16x32_bf16 v[30:33], v[66:69], v[42:45], v[34:37]
	s_nop 2
	v_mul_f32_e64 v36, v156, s64
	v_mul_f32_e64 v37, v157, s64
	v_pk_mul_f32 v[34:35], v[154:155], s[64:65] op_sel_hi:[1,0]
	s_waitcnt vmcnt(26) lgkmcnt(0)
	v_mfma_f32_16x16x32_bf16 v[30:33], v[74:77], v[46:49], v[30:33]
	s_waitcnt vmcnt(25)
	v_mfma_f32_16x16x32_bf16 v[34:37], v[70:73], v[42:45], v[34:37]
	s_waitcnt vmcnt(24)
	v_mfma_f32_16x16x32_bf16 v[146:149], v[78:81], v[46:49], v[34:37]
	s_waitcnt vmcnt(23)
	v_mfma_f32_16x16x32_bf16 v[34:37], v[82:85], v[42:45], v[50:53]
	s_waitcnt vmcnt(22)
	v_mfma_f32_16x16x32_bf16 v[150:153], v[86:89], v[46:49], v[34:37]
	s_nop 5
	v_cvt_pk_bf16_f32 v34, v146, v147
	v_cvt_pk_bf16_f32 v35, v148, v149
	v_cvt_pk_bf16_f32 v36, v150, v151
	v_cvt_pk_bf16_f32 v37, v152, v153
	ds_write2_b64 v234, v[34:35], v[36:37] offset1:4
	v_add_u32_e32 v34, 0x100, v192
	v_ashrrev_i32_e32 v35, 31, v34
	v_lshlrev_b64 v[34:35], 12, v[34:35]
	v_lshl_add_u64 v[34:35], v[190:191], 0, v[34:35]
	v_add_co_u32_e32 v36, vcc, s30, v34
	global_store_dword v[34:35], v30, off
	s_nop 0
	v_addc_co_u32_e32 v37, vcc, 0, v35, vcc
	v_add_co_u32_e32 v30, vcc, s31, v34
	global_store_dword v[36:37], v31, off offset:-4096
	global_store_dword v[36:37], v32, off
	v_addc_co_u32_e32 v31, vcc, 0, v35, vcc
	global_store_dword v[30:31], v33, off
	v_add_co_u32_e32 v30, vcc, s56, v214
	s_waitcnt lgkmcnt(0)
	s_barrier
	s_nop 0
	v_addc_co_u32_e32 v31, vcc, 0, v215, vcc
	v_add_co_u32_e32 v34, vcc, s57, v214
	global_load_dwordx4 v[30:33], v[30:31], off
	s_nop 0
	v_addc_co_u32_e32 v35, vcc, 0, v215, vcc
	v_add_co_u32_e32 v42, vcc, s56, v216
	global_load_dwordx4 v[34:37], v[34:35], off
	s_nop 0
	v_addc_co_u32_e32 v43, vcc, 0, v217, vcc
	global_load_dwordx4 v[46:49], v[42:43], off
	v_add_co_u32_e32 v42, vcc, s57, v216
	s_nop 1
	v_addc_co_u32_e32 v43, vcc, 0, v217, vcc
	ds_read_b128 v[214:217], v237
	ds_read_b128 v[250:253], v237 offset:64
	global_load_dwordx4 v[50:53], v[42:43], off
	v_add_co_u32_e32 v42, vcc, s56, v218
	s_nop 1
	v_addc_co_u32_e32 v43, vcc, 0, v219, vcc
	v_add_co_u32_e32 v54, vcc, s57, v218
	global_load_dwordx4 v[42:45], v[42:43], off
	s_nop 0
	v_addc_co_u32_e32 v55, vcc, 0, v219, vcc
	v_add_co_u32_e32 v58, vcc, s56, v220
	global_load_dwordx4 v[54:57], v[54:55], off
	s_nop 0
	v_addc_co_u32_e32 v59, vcc, 0, v221, vcc
	v_add_co_u32_e32 v62, vcc, s57, v220
	global_load_dwordx4 v[58:61], v[58:59], off
	s_nop 0
	v_addc_co_u32_e32 v63, vcc, 0, v221, vcc
	v_add_co_u32_e32 v66, vcc, s58, v222
	global_load_dwordx4 v[62:65], v[62:63], off
	s_nop 0
	v_addc_co_u32_e32 v67, vcc, 0, v223, vcc
	global_load_dword v157, v[66:67], off
	global_load_dword v154, v[66:67], off offset:256
	global_load_dword v155, v[66:67], off offset:512
	global_load_dword v156, v[66:67], off offset:768
	v_add_co_u32_e32 v66, vcc, s59, v224
	s_nop 1
	v_addc_co_u32_e32 v67, vcc, 0, v225, vcc
	global_load_dwordx4 v[86:89], v[66:67], off
	v_add_co_u32_e32 v66, vcc, s59, v226
	s_nop 1
	v_addc_co_u32_e32 v67, vcc, 0, v227, vcc
	global_load_dwordx4 v[74:77], v[66:67], off
	v_add_co_u32_e32 v66, vcc, s60, v228
	s_nop 1
	v_addc_co_u32_e32 v67, vcc, 0, v229, vcc
	v_add_co_u32_e32 v68, vcc, s60, v230
	global_load_dwordx4 v[70:73], v[66:67], off
	s_nop 0
	v_addc_co_u32_e32 v69, vcc, 0, v231, vcc
	v_add_co_u32_e32 v78, vcc, s60, v232
	global_load_dwordx4 v[82:85], v[68:69], off
	s_nop 0
	global_load_dwordx4 v[66:69], v[66:67], off offset:1024
	v_addc_co_u32_e32 v79, vcc, 0, v233, vcc
	global_load_dwordx4 v[78:81], v[78:79], off

	s_waitcnt lgkmcnt(0)
	v_mfma_f32_16x16x32_bf16 v[90:93], v[90:93], v[214:217], 0
	v_mfma_f32_16x16x32_bf16 v[94:97], v[94:97], v[214:217], 0

; DEV void gdn_scan_item(const Params& p, int item, unsigned char* lds) {
;     ...
;     LOAD_E(E0, 0); LOAD_L(L0, 0); LOAD_E(E1, 1);
;     __syncthreads();
;     for (int ch = 0; ch < 30; ch += 6) {
;         SCAN_STEP(E0, E2, L0, L1, ch);     SCAN_STEP(E1, E0, L1, L0, ch + 1); SCAN_STEP(E2, E1, L0, L1, ch + 2);
;         SCAN_STEP(E0, E2, L1, L0, ch + 3); SCAN_STEP(E1, E0, L0, L1, ch + 4); SCAN_STEP(E2, E1, L1, L0, ch + 5);
;     }
;     SCAN_STEP(E0, E2, L0, L1, 30); SCAN_STEP(E1, E0, L1, L0, 31);
	s_waitcnt lgkmcnt(0)
	v_mfma_f32_16x16x32_bf16 v[90:93], v[98:101], v[250:253], v[90:93]
	ds_read_b128 v[98:101], v237 offset:128
	v_mfma_f32_16x16x32_bf16 v[94:97], v[102:105], v[250:253], v[94:97]
	s_waitcnt lgkmcnt(0)
	v_mfma_f32_16x16x32_bf16 v[90:93], v[106:109], v[98:101], v[90:93]
	v_mul_f32_e64 v108, v152, s62
	v_mul_f32_e64 v109, v153, s62
	v_pk_mul_f32 v[106:107], v[150:151], s[62:63] op_sel_hi:[1,0]
	v_mfma_f32_16x16x32_bf16 v[94:97], v[110:113], v[98:101], v[94:97]
	ds_read_b128 v[98:101], v237 offset:192
	s_waitcnt lgkmcnt(0)
	v_mfma_f32_16x16x32_bf16 v[90:93], v[114:117], v[98:101], v[90:93]
	v_mfma_f32_16x16x32_bf16 v[94:97], v[118:121], v[98:101], v[94:97]
	s_nop 6
	v_sub_f32_e32 v93, v244, v93
	v_sub_f32_e32 v92, v243, v92
	v_sub_f32_e32 v91, v242, v91
	v_sub_f32_e32 v90, v241, v90
	v_cvt_pk_bf16_f32 v90, v90, v91
	v_cvt_pk_bf16_f32 v91, v92, v93
	ds_write_b64 v236, v[90:91] offset:4352
	s_waitcnt lgkmcnt(0)
	s_barrier
	ds_read_b128 v[90:93], v235 offset:4352
	ds_read_b128 v[102:105], v235 offset:4416
	s_waitcnt vmcnt(27) lgkmcnt(1)
	v_mfma_f32_16x16x32_bf16 v[94:97], v[122:125], v[90:93], v[94:97]
	s_waitcnt vmcnt(26) lgkmcnt(0)
	v_mfma_f32_16x16x32_bf16 v[98:101], v[130:133], v[102:105], v[94:97]
	s_nop 5
	v_mul_f32_e64 v96, v148, s62
	v_mul_f32_e64 v97, v149, s62
	v_pk_mul_f32 v[94:95], v[146:147], s[62:63] op_sel_hi:[1,0]
	s_mov_b32 s62, s61
	s_waitcnt vmcnt(25)
	v_mfma_f32_16x16x32_bf16 v[94:97], v[126:129], v[90:93], v[94:97]
	s_waitcnt vmcnt(23)
	v_mfma_f32_16x16x32_bf16 v[90:93], v[138:141], v[90:93], v[106:109]
	v_mfma_f32_16x16x32_bf16 v[94:97], v[134:137], v[102:105], v[94:97]
	s_waitcnt vmcnt(22)
	v_mfma_f32_16x16x32_bf16 v[90:93], v[142:145], v[102:105], v[90:93]
	s_nop 5
	v_cvt_pk_bf16_f32 v102, v94, v95
	v_cvt_pk_bf16_f32 v103, v96, v97
	v_cvt_pk_bf16_f32 v104, v90, v91
	v_cvt_pk_bf16_f32 v105, v92, v93
	ds_write2_b64 v234, v[102:103], v[104:105] offset1:4
	v_add_u32_e32 v102, 0x140, v192
	v_ashrrev_i32_e32 v103, 31, v102
	v_lshlrev_b64 v[102:103], 12, v[102:103]
	v_lshl_add_u64 v[102:103], v[190:191], 0, v[102:103]
	v_add_co_u32_e32 v104, vcc, s30, v102
	global_store_dword v[102:103], v98, off
	s_nop 0
	v_addc_co_u32_e32 v105, vcc, 0, v103, vcc
	v_add_co_u32_e32 v98, vcc, s31, v102
	global_store_dword v[104:105], v99, off offset:-4096
	global_store_dword v[104:105], v100, off
	v_addc_co_u32_e32 v99, vcc, 0, v103, vcc
	global_store_dword v[98:99], v101, off
	s_waitcnt lgkmcnt(0)
	s_barrier
	v_add_u32_e32 v192, 0x180, v192
	s_cbranch_scc1 .LBB0_888
	ds_read_b128 v[98:101], v237
	ds_read_b128 v[102:105], v237 offset:64
	s_add_u32 s8, s12, 0x3e000
	s_addc_u32 s9, s13, 0
	v_lshl_add_u64 v[106:107], s[8:9], 0, v[180:181]
	s_waitcnt lgkmcnt(1)
	v_mfma_f32_16x16x32_bf16 v[18:21], v[18:21], v[98:101], 0
	v_or_b32_e32 v108, 0x400, v184
	v_add3_u32 v1, v1, s24, v179
	s_movk_i32 s13, 0x2000
	v_mfma_f32_16x16x32_bf16 v[38:41], v[38:41], v[98:101], 0
	v_lshl_add_u64 v[98:99], s[8:9], 0, v[182:183]
	s_add_u32 s8, s10, 0x7c000
	s_addc_u32 s9, s11, 0
	s_waitcnt lgkmcnt(0)
	v_mfma_f32_16x16x32_bf16 v[6:9], v[6:9], v[102:105], v[18:21]
	v_lshl_add_u64 v[100:101], s[8:9], 0, v[184:185]
	v_lshl_add_u64 v[110:111], s[8:9], 0, v[188:189]
	s_lshl_b32 s10, s23, 2
	ds_read_b128 v[18:21], v237 offset:128
	v_mfma_f32_16x16x32_bf16 v[2:5], v[2:5], v[102:105], v[38:41]
	s_nop 2
	global_load_dwordx4 v[38:41], v[98:99], off
	s_nop 0
	global_load_dwordx4 v[98:101], v[100:101], off
	ds_read_b128 v[102:105], v237 offset:192
	s_movk_i32 s16, 0x3000
	s_waitcnt lgkmcnt(1)
	v_mfma_f32_16x16x32_bf16 v[6:9], v[26:29], v[18:21], v[6:9]
	global_load_dwordx4 v[26:29], v[106:107], off
	s_nop 0
	global_load_dwordx4 v[106:109], v108, s[8:9]
	v_readlane_b32 s12, v177, 31
	s_lshl_b64 s[4:5], s[4:5], 7
	v_mfma_f32_16x16x32_bf16 v[2:5], v[14:17], v[18:21], v[2:5]
	v_lshl_add_u64 v[18:19], s[8:9], 0, v[186:187]
	global_load_dwordx4 v[14:17], v[110:111], off
	s_nop 0
	global_load_dwordx4 v[18:21], v[18:19], off
	v_readlane_b32 s8, v177, 30
	s_waitcnt lgkmcnt(0)
	v_mfma_f32_16x16x32_bf16 v[6:9], v[22:25], v[102:105], v[6:9]
	v_ashrrev_i32_e32 v177, 31, v176
	v_pk_mul_f32 v[24:25], v[96:97], s[8:9] op_sel_hi:[1,0]
	v_pk_mul_f32 v[22:23], v[94:95], s[8:9] op_sel_hi:[1,0]
	v_mfma_f32_16x16x32_bf16 v[2:5], v[10:13], v[102:105], v[2:5]
	s_nop 3
	v_sub_f32_e32 v9, v240, v9
	v_sub_f32_e32 v8, v239, v8
	v_sub_f32_e32 v7, v238, v7
	v_sub_f32_e32 v6, v193, v6
	v_cvt_pk_bf16_f32 v6, v6, v7
	v_cvt_pk_bf16_f32 v7, v8, v9
	ds_write_b64 v236, v[6:7] offset:4352
	s_waitcnt lgkmcnt(0)
	s_barrier
; DEV void gdn_scan_item(const Params& p, int item, unsigned char* lds) {
;     ...
;     LOAD_E(E0, 0); LOAD_L(L0, 0); LOAD_E(E1, 1);
;     __syncthreads();
;     for (int ch = 0; ch < 30; ch += 6) {
;         SCAN_STEP(E0, E2, L0, L1, ch);     SCAN_STEP(E1, E0, L1, L0, ch + 1); SCAN_STEP(E2, E1, L0, L1, ch + 2);
;         SCAN_STEP(E0, E2, L1, L0, ch + 3); SCAN_STEP(E1, E0, L0, L1, ch + 4); SCAN_STEP(E2, E1, L1, L0, ch + 5);
;     }
;     SCAN_STEP(E0, E2, L0, L1, 30); SCAN_STEP(E1, E0, L1, L0, 31);
;     ...
;     {
;         float* dp = p.out + O_DP + ((size_t)bh * 128 + w * 32 + fq * 4) * 128 + s * 16 + fr;
; #pragma unroll
;         for (int e = 0; e < 4; ++e) { dp[e * 128] = S0[e]; dp[(16 + e) * 128] = S1[e]; }
;     }
	ds_read_b128 v[6:9], v235 offset:4352
	ds_read_b128 v[10:13], v235 offset:4416
	s_waitcnt vmcnt(13) lgkmcnt(1)
	v_mfma_f32_16x16x32_bf16 v[22:25], v[70:73], v[6:9], v[22:25]
	v_mul_f32_e64 v72, v92, s8
	v_mul_f32_e64 v73, v93, s8
	v_pk_mul_f32 v[70:71], v[90:91], s[8:9] op_sel_hi:[1,0]
	s_mov_b32 s9, 0
	v_mfma_f32_16x16x32_bf16 v[2:5], v[86:89], v[6:9], v[2:5]
	s_lshl_b32 s8, s22, 2
	s_mov_b32 s11, s9
	s_waitcnt vmcnt(11)
	v_mfma_f32_16x16x32_bf16 v[6:9], v[66:69], v[6:9], v[70:73]
	s_waitcnt lgkmcnt(0)
	v_mfma_f32_16x16x32_bf16 v[22:25], v[82:85], v[10:13], v[22:25]
	s_waitcnt vmcnt(10)
	v_mfma_f32_16x16x32_bf16 v[6:9], v[78:81], v[10:13], v[6:9]
	v_mfma_f32_16x16x32_bf16 v[2:5], v[74:77], v[10:13], v[2:5]
	v_add_u32_e32 v10, 0x780, v1
	v_ashrrev_i32_e32 v11, 31, v10
	v_lshlrev_b64 v[10:11], 12, v[10:11]
	v_lshl_add_u64 v[10:11], s[6:7], 0, v[10:11]
	s_nop 0
	v_cvt_pk_bf16_f32 v66, v22, v23
	v_cvt_pk_bf16_f32 v67, v24, v25
	v_cvt_pk_bf16_f32 v68, v6, v7
	v_cvt_pk_bf16_f32 v69, v8, v9
	v_lshl_add_u64 v[10:11], v[10:11], 0, s[8:9]
	ds_write2_b64 v234, v[66:67], v[68:69] offset1:4
	v_lshl_add_u64 v[10:11], v[10:11], 0, s[10:11]
	v_lshlrev_b32_e32 v66, 2, v178
	v_mov_b32_e32 v67, 0
	v_lshl_add_u64 v[10:11], v[10:11], 0, v[66:67]
	v_add_co_u32_e32 v12, vcc, s13, v10
	global_store_dword v[10:11], v2, off
	s_nop 0
	v_addc_co_u32_e32 v13, vcc, 0, v11, vcc
	v_add_co_u32_e32 v2, vcc, s16, v10
	global_store_dword v[12:13], v3, off offset:-4096
	global_store_dword v[12:13], v4, off
	v_addc_co_u32_e32 v3, vcc, 0, v11, vcc
	global_store_dword v[2:3], v5, off
	s_waitcnt lgkmcnt(0)
	s_barrier
	ds_read_b128 v[2:5], v237
	ds_read_b128 v[10:13], v237 offset:64
	s_waitcnt lgkmcnt(1)
	v_mfma_f32_16x16x32_bf16 v[30:33], v[30:33], v[2:5], 0
	v_mul_f32_e64 v24, v24, s12
	v_mul_f32_e64 v25, v25, s12
	v_pk_mul_f32 v[22:23], v[22:23], s[12:13] op_sel_hi:[1,0]
	v_pk_mul_f32 v[8:9], v[8:9], s[12:13] op_sel_hi:[1,0]
	v_mfma_f32_16x16x32_bf16 v[2:5], v[34:37], v[2:5], 0
	v_mul_f32_e64 v6, v6, s12
	v_mul_f32_e64 v7, v7, s12
	s_waitcnt lgkmcnt(0)
	v_mfma_f32_16x16x32_bf16 v[30:33], v[46:49], v[10:13], v[30:33]
	v_mfma_f32_16x16x32_bf16 v[2:5], v[50:53], v[10:13], v[2:5]
	ds_read_b128 v[10:13], v237 offset:128
	ds_read_b128 v[34:37], v237 offset:192
	s_waitcnt lgkmcnt(1)
	v_mfma_f32_16x16x32_bf16 v[30:33], v[42:45], v[10:13], v[30:33]
	v_mfma_f32_16x16x32_bf16 v[2:5], v[54:57], v[10:13], v[2:5]
	s_waitcnt lgkmcnt(0)
	v_mfma_f32_16x16x32_bf16 v[10:13], v[58:61], v[34:37], v[30:33]
	v_mfma_f32_16x16x32_bf16 v[2:5], v[62:65], v[34:37], v[2:5]
	s_nop 6
	v_sub_f32_e32 v13, v156, v13
	v_sub_f32_e32 v12, v155, v12
	v_sub_f32_e32 v11, v154, v11
	v_sub_f32_e32 v10, v157, v10
	v_cvt_pk_bf16_f32 v10, v10, v11
	v_cvt_pk_bf16_f32 v11, v12, v13
	ds_write_b64 v236, v[10:11] offset:4352
	s_waitcnt lgkmcnt(0)
	s_barrier
	ds_read_b128 v[10:13], v235 offset:4352
	ds_read_b128 v[30:33], v235 offset:4416
	s_waitcnt vmcnt(8) lgkmcnt(1)
	v_mfma_f32_16x16x32_bf16 v[22:25], v[98:101], v[10:13], v[22:25]
	s_waitcnt vmcnt(6)
	v_mfma_f32_16x16x32_bf16 v[6:9], v[106:109], v[10:13], v[6:9]
	s_waitcnt vmcnt(5) lgkmcnt(0)
	v_mfma_f32_16x16x32_bf16 v[14:17], v[14:17], v[30:33], v[22:25]
	s_waitcnt vmcnt(4)
	v_mfma_f32_16x16x32_bf16 v[6:9], v[18:21], v[30:33], v[6:9]
	v_mfma_f32_16x16x32_bf16 v[2:5], v[26:29], v[10:13], v[2:5]
	s_nop 4
	v_cvt_pk_bf16_f32 v10, v14, v15
	v_cvt_pk_bf16_f32 v11, v16, v17
	v_cvt_pk_bf16_f32 v12, v6, v7
	v_cvt_pk_bf16_f32 v13, v8, v9
	ds_write2_b64 v234, v[10:11], v[12:13] offset1:4
	v_add_u32_e32 v10, 0x7c0, v1
	v_ashrrev_i32_e32 v11, 31, v10
	v_lshlrev_b64 v[10:11], 12, v[10:11]
	v_lshl_add_u64 v[10:11], s[6:7], 0, v[10:11]
	v_lshl_add_u64 v[10:11], v[10:11], 0, s[8:9]
	v_mfma_f32_16x16x32_bf16 v[2:5], v[38:41], v[30:33], v[2:5]
	v_lshl_add_u64 v[10:11], v[10:11], 0, s[10:11]
	v_lshl_add_u64 v[10:11], v[10:11], 0, v[66:67]
	v_add_co_u32_e32 v12, vcc, s13, v10
	s_nop 1
	v_addc_co_u32_e32 v13, vcc, 0, v11, vcc
	s_nop 1
	global_store_dword v[10:11], v2, off
	v_add_co_u32_e32 v2, vcc, s16, v10
	global_store_dword v[12:13], v3, off offset:-4096
	global_store_dword v[12:13], v4, off
	v_addc_co_u32_e32 v3, vcc, 0, v11, vcc
	global_store_dword v[2:3], v5, off
	s_waitcnt lgkmcnt(0)
	s_barrier
	s_load_dwordx2 s[6:7], s[0:1], 0xc0
	v_lshl_add_u64 v[2:3], s[4:5], 0, v[176:177]
	v_or_b32_e32 v2, v2, v179
	v_lshlrev_b64 v[2:3], 9, v[2:3]
	s_mov_b64 s[4:5], 0x5400000
	s_waitcnt lgkmcnt(0)
	v_lshl_add_u64 v[2:3], s[6:7], 0, v[2:3]
	v_lshl_add_u64 v[2:3], v[2:3], 0, s[10:11]
	v_lshl_add_u64 v[2:3], v[2:3], 0, v[66:67]
	v_lshl_add_u64 v[4:5], v[2:3], 0, s[4:5]
	s_mov_b32 s4, 0x5400000
	v_add_co_u32_e32 v10, vcc, s4, v2
	s_nop 1
	v_addc_co_u32_e32 v11, vcc, 0, v3, vcc
	v_add_co_u32_e32 v2, vcc, 0x5402000, v2
	global_store_dword v[10:11], v14, off
	s_nop 0
	v_addc_co_u32_e32 v3, vcc, 0, v3, vcc
	global_store_dword v[2:3], v6, off
	global_store_dword v[4:5], v15, off offset:512
	global_store_dword v[2:3], v7, off offset:512
	global_store_dword v[4:5], v16, off offset:1024
	global_store_dword v[2:3], v8, off offset:1024
	global_store_dword v[4:5], v17, off offset:1536
	global_store_dword v[2:3], v9, off offset:1536
	v_mov_b32_e32 v252, v254
	s_barrier

; __global__ void __launch_bounds__(512) hymba_fwd(Params p) {
;     __shared__ __attribute__((aligned(16))) unsigned char lds[131072];
	.amdhsa_kernel _Z9hymba_fwd6Params
		.amdhsa_group_segment_fixed_size 131088
		.amdhsa_private_segment_fixed_size 0
		.amdhsa_kernarg_size 472
		.amdhsa_user_sgpr_count 2
		.amdhsa_user_sgpr_dispatch_ptr 0
		.amdhsa_user_sgpr_queue_ptr 0
		.amdhsa_user_sgpr_kernarg_segment_ptr 1
		.amdhsa_user_sgpr_dispatch_id 0
		.amdhsa_user_sgpr_kernarg_preload_length 0
		.amdhsa_user_sgpr_kernarg_preload_offset 0
		.amdhsa_user_sgpr_private_segment_size 0
		.amdhsa_uses_dynamic_stack 0
		.amdhsa_enable_private_segment 0
		.amdhsa_system_sgpr_workgroup_id_x 1
		.amdhsa_system_sgpr_workgroup_id_y 0
		.amdhsa_system_sgpr_workgroup_id_z 0
		.amdhsa_system_sgpr_workgroup_info 0
		.amdhsa_system_vgpr_workitem_id 0
		.amdhsa_next_free_vgpr 256
		.amdhsa_next_free_sgpr 100
		.amdhsa_accum_offset 256
		.amdhsa_reserve_vcc 1
		.amdhsa_float_round_mode_32 0
		.amdhsa_float_round_mode_16_64 0
		.amdhsa_float_denorm_mode_32 3
		.amdhsa_float_denorm_mode_16_64 3
		.amdhsa_dx10_clamp 1
		.amdhsa_ieee_mode 1
		.amdhsa_fp16_overflow 0
		.amdhsa_tg_split 0
		.amdhsa_exception_fp_ieee_invalid_op 0
		.amdhsa_exception_fp_denorm_src 0
		.amdhsa_exception_fp_ieee_div_zero 0
		.amdhsa_exception_fp_ieee_overflow 0
		.amdhsa_exception_fp_ieee_underflow 0
		.amdhsa_exception_fp_ieee_inexact 0
		.amdhsa_exception_int_div_zero 0
	.end_amdhsa_kernel

; __global__ void __launch_bounds__(512) hymba_fwd(Params p) {
;     __shared__ __attribute__((aligned(16))) unsigned char lds[131072];
amdhsa.kernels:
  - .agpr_count:     0
    .args:
      - .offset:         0
        .size:           216
        .value_kind:     by_value
      - .offset:         216
        .size:           4
        .value_kind:     hidden_block_count_x
      - .offset:         220
        .size:           4
        .value_kind:     hidden_block_count_y
      - .offset:         224
        .size:           4
        .value_kind:     hidden_block_count_z
      - .offset:         228
        .size:           2
        .value_kind:     hidden_group_size_x
      - .offset:         230
        .size:           2
        .value_kind:     hidden_group_size_y
      - .offset:         232
        .size:           2
        .value_kind:     hidden_group_size_z
      - .offset:         234
        .size:           2
        .value_kind:     hidden_remainder_x
      - .offset:         236
        .size:           2
        .value_kind:     hidden_remainder_y
      - .offset:         238
        .size:           2
        .value_kind:     hidden_remainder_z
      - .offset:         256
        .size:           8
        .value_kind:     hidden_global_offset_x
      - .offset:         264
        .size:           8
        .value_kind:     hidden_global_offset_y
      - .offset:         272
        .size:           8
        .value_kind:     hidden_global_offset_z
      - .offset:         280
        .size:           2
        .value_kind:     hidden_grid_dims
    .group_segment_fixed_size: 131088
    .kernarg_segment_align: 8
    .kernarg_segment_size: 472
    .language:       OpenCL C
    .language_version:
      - 2
      - 0
    .max_flat_workgroup_size: 512
    .name:           _Z9hymba_fwd6Params
    .private_segment_fixed_size: 0
    .sgpr_count:     106
    .sgpr_spill_count: 4
    .symbol:         _Z9hymba_fwd6Params.kd
    .uniform_work_group_size: 1
    .uses_dynamic_stack: false
    .vgpr_count:     256
    .vgpr_spill_count: 0
    .wavefront_size: 64
